# k17 + layer-0 input-projection phase rebalanced: workgroups <128 compute the gates for the whole row block, workgroups >=128 take the fourth-round tiles
# speedup vs baseline: 1.0004x; 1.0004x over previous
; __global__ void __launch_bounds__(512, 2) mk_fwd(Args a) {
;     ...
;     for (int ph = a.ph_lo; ph < a.ph_hi; ++ph) {
;         if (ph == PH_PER_LAYER || ph == 2 * PH_PER_LAYER - 1) continue;
;         run_phase(ph, lds);
;         if (ph + 1 < a.ph_hi) xcd_barrier(xb);
.Lnot5:
	s_cmp_lg_u32 s100, 4
	s_cbranch_scc1 .Lnot4c
	s_cmp_lg_u32 s22, 4
	s_cbranch_scc1 .Lnot4c
	s_cmpk_lt_u32 s19, 0x80
	s_cbranch_scc1 .Lnot4c
	s_mov_b32 s100, 7
	s_branch .LBB0_22

; __device__ __forceinline__ void run_phase(int ph, LAS unsigned char* lds) {
;     ...
;     const int l = ph / PH_PER_LAYER, p = ph % PH_PER_LAYER;
;     float* stats = (float*)(ws + OFF_STATS);
;     const float* mur = (const float*)(ws + OFF_MUR);
;     const float* mu_in = l > 0 ? mur + (size_t)((l - 1) * 3 + 2) * T_ * 2 : nullptr;
;     const float* mu0 = mur + (size_t)(l * 3 + 0) * T_ * 2; const float* mu1 = mur + (size_t)(l * 3 + 1) * T_ * 2;
;     float* st0 = stats + (size_t)(l * 3 + 0) * T_ * 32; float* st1 = stats + (size_t)(l * 3 + 1) * T_ * 32; float* st2 = stats + (size_t)(l * 3 + 2) * T_ * 32;
;     const float* ln_g = a.in[5]; const float* ln_b = a.in[6];
;     pg8::StaticOrder S;
;     switch (p) {
;     case 0: if (PH_ENABLED(0)) { if (l == 0) pro_part(a, tb, 0, 0, tb.bid, tb.G, lds); } break;
;     case 1: if (PH_ENABLED(1)) { pg8::Gemm g{(const bf16_t*)(ws + OFF_YB), (const bf16_t*)(ws + OFF_WGU0), T_, 2 * FF_, D_}; S.init(g.M, g.N, tb.G, tb.bid);
;         EpiGU E{(bf16_t*)(ws + OFF_H), mu_in, (const float*)(ws + OFF_C12GU0), (const float*)(ws + OFF_C12GU0) + 5632}; pg8::gemm_phase(tb, lds, g, S, E); } break;
;     case 2: if (PH_ENABLED(2)) { pg8::Gemm g{(const bf16_t*)(ws + OFF_H), (const bf16_t*)(ws + OFF_WDN0), T_, D_, FF_}; S.init(g.M, g.N, tb.G, tb.bid);
;         EpiRes E{nullptr, (bf16_t*)(ws + OFF_YB), mu_in, l > 0 ? ln_g + ((l - 1) * 3 + 2) * D_ : nullptr, l > 0 ? ln_b + ((l - 1) * 3 + 2) * D_ : nullptr, st0, 0.5f}; pg8::gemm_phase(tb, lds, g, S, E); } break;
;     case 3: if (PH_ENABLED(3)) phase_statsfin(a, tb, l * 3 + 0); break;
;     case 4: if (PH_ENABLED(4)) { pg8::Gemm g{(const bf16_t*)(ws + OFF_YB), (const bf16_t*)(ws + OFF_WIN), T_, NING_, D_}; S.init(g.M, g.N, tb.G, tb.bid);
;         EpiIn E{mu0, (const float*)(ws + OFF_C12IN), (const float*)(ws + OFF_C12IN) + 3584, (bf16_t*)(ws + OFF_QK), (bf16_t*)(ws + OFF_VT), (bf16_t*)(ws + OFF_PC), (bf16_t*)(ws + OFF_Z)}; pg8::gemm_phase(tb, lds, g, S, E);
;         } break;
.LBB0_30:
	s_mul_hi_i32 s2, s22, 0x92492493
	s_add_i32 s2, s2, s22
	s_lshr_b32 s3, s2, 31
	s_ashr_i32 s2, s2, 3
	s_add_i32 s50, s2, s3
	s_mul_i32 s2, s50, 14
	s_mov_b64 s[6:7], s[22:23]
	s_sub_i32 s8, s22, s2
	s_movk_i32 s101, 0x37f
	s_cmp_eq_u32 s100, 7
	s_cbranch_scc0 .Lno_passc
	s_add_i32 s68, s19, 0x280
	s_branch .Lsf_nohook
.Lno_passc:
	s_cmpk_lg_u32 s56, 0x100
	s_cbranch_scc1 .Lsf_nohook
	s_cmp_eq_u32 s8, 3
	s_cbranch_scc1 .Lsf_hook
	s_cmp_eq_u32 s8, 10
	s_cbranch_scc1 .Lsf_hook
	s_cmp_eq_u32 s8, 13
	s_cbranch_scc1 .Lsf_hook
	s_cmp_eq_u32 s8, 4
	s_cbranch_scc0 .Lgp_no
	s_cmp_eq_u32 s100, 0
	s_cbranch_scc0 .Lgp_second
	s_mov_b32 s100, 3
	s_mov_b32 s8, 5
	s_branch .Lsf_nohook
.Lgp_second:
	s_movk_i32 s101, 0x2ff
	s_branch .Lsf_nohook

; __device__ __forceinline__ void phase_gates(ArgsRef a, const Tb tb, int l) {
;     ...
;     const int wv = tb.tid >> 6, lane = tb.tid & 63;
;     const int gw = tb.bid * 8 + wv, GW = tb.G * 8;
;     for (int t = gw; t < T_; t += GW) {
.LBB0_1185:
	s_and_b64 vcc, exec, s[2:3]
	s_mov_b32 s73, s65
	s_cbranch_vccz .LBB0_1255
	v_readlane_b32 s38, v254, 42
	v_ashrrev_i32_e32 v198, 6, v196
	s_lshl_b32 s16, s38, 3
	v_readlane_b32 s14, v254, 36
	s_movk_i32 s36, 0x3fff
	s_cmpk_lg_u32 s14, 0x100
	s_cbranch_scc1 .Lgt_std
	s_and_b32 s16, s38, 7
	s_lshl_b32 s16, s16, 3
	s_bfe_u32 s14, s38, 0x30003
	s_add_i32 s16, s16, s14
	s_lshl_b32 s16, s16, 8
	s_lshr_b32 s14, s38, 6
	s_lshl_b32 s14, s14, 6
	s_add_i32 s16, s16, s14
	s_add_i32 s36, s16, 63
	v_readlane_b32 s14, v254, 40
	s_cmp_lg_u32 s14, 0
	s_cbranch_scc1 .Lgt_std
	s_cmp_eq_u32 s100, 3
	s_cbranch_scc0 .Lgt_std
	s_lshr_b32 s14, s38, 6
	s_lshl_b32 s14, s14, 6
	s_sub_i32 s16, s16, s14
	s_movk_i32 s36, 0x7fff
	s_cmpk_lt_u32 s38, 0x80
	s_cbranch_scc0 .Lgt_none
	s_lshl_b32 s14, s14, 1
	s_add_i32 s16, s16, s14
	s_add_i32 s36, s16, 127
	s_branch .Lgt_std
.Lgt_none:
	s_movk_i32 s16, 0x4000
